# loop-tail SALU (ring rotation, counters) and the P.V LDS base moved into the hazard window after the last QK MFMA, replacing s_nop 9
# baseline (speedup 1.0000x reference)
.LBB0_513:
	s_lshl_b32 s4, s76, 14
	v_add3_u32 v236, s4, v221, v220
	ds_read_b128 v[192:195], v236
	ds_read_b128 v[196:199], v236 offset:8192
	v_add3_u32 v236, s4, v222, v220
	ds_read_b128 v[200:203], v236
	ds_read_b128 v[204:207], v236 offset:8192
	v_add3_u32 v236, s4, v223, v220
	ds_read_b128 v[240:243], v236
	ds_read_b128 v[244:247], v236 offset:8192
	v_add3_u32 v236, s4, v224, v220
	ds_read_b128 v[248:251], v236
	ds_read_b128 v[252:255], v236 offset:8192
	s_waitcnt lgkmcnt(7)
	v_mfma_f32_32x32x16_bf16 v[144:159], v[192:195], v[160:163], 0
	s_waitcnt lgkmcnt(6)
	v_mfma_f32_32x32x16_bf16 v[128:143], v[196:199], v[160:163], 0
	v_add3_u32 v236, s4, v225, v220
	ds_read_b128 v[192:195], v236
	ds_read_b128 v[196:199], v236 offset:8192
	s_waitcnt lgkmcnt(7)
	v_mfma_f32_32x32x16_bf16 v[144:159], v[200:203], v[164:167], v[144:159]
	s_waitcnt lgkmcnt(6)
	v_mfma_f32_32x32x16_bf16 v[128:143], v[204:207], v[164:167], v[128:143]
	v_add3_u32 v236, s4, v227, v220
	ds_read_b128 v[200:203], v236
	ds_read_b128 v[204:207], v236 offset:8192
	s_waitcnt lgkmcnt(7)
	v_mfma_f32_32x32x16_bf16 v[144:159], v[240:243], v[168:171], v[144:159]
	s_waitcnt lgkmcnt(6)
	v_mfma_f32_32x32x16_bf16 v[128:143], v[244:247], v[168:171], v[128:143]
	v_add3_u32 v236, s4, v228, v220
	ds_read_b128 v[240:243], v236
	ds_read_b128 v[244:247], v236 offset:8192
	s_waitcnt lgkmcnt(7)
	v_mfma_f32_32x32x16_bf16 v[144:159], v[248:251], v[172:175], v[144:159]
	s_waitcnt lgkmcnt(6)
	v_mfma_f32_32x32x16_bf16 v[128:143], v[252:255], v[172:175], v[128:143]
	v_add3_u32 v236, s4, v229, v220
	ds_read_b128 v[248:251], v236
	ds_read_b128 v[252:255], v236 offset:8192
	s_waitcnt lgkmcnt(7)
	v_mfma_f32_32x32x16_bf16 v[144:159], v[192:195], v[176:179], v[144:159]
	s_waitcnt lgkmcnt(6)
	v_mfma_f32_32x32x16_bf16 v[128:143], v[196:199], v[176:179], v[128:143]
	s_waitcnt lgkmcnt(5)
	v_mfma_f32_32x32x16_bf16 v[144:159], v[200:203], v[180:183], v[144:159]
	s_waitcnt lgkmcnt(4)
	v_mfma_f32_32x32x16_bf16 v[128:143], v[204:207], v[180:183], v[128:143]
	s_waitcnt lgkmcnt(3)
	v_mfma_f32_32x32x16_bf16 v[144:159], v[240:243], v[184:187], v[144:159]
	s_waitcnt lgkmcnt(2)
	v_mfma_f32_32x32x16_bf16 v[128:143], v[244:247], v[184:187], v[128:143]
	s_waitcnt lgkmcnt(1)
	v_mfma_f32_32x32x16_bf16 v[144:159], v[248:251], v[188:191], v[144:159]
	s_waitcnt lgkmcnt(0)
	v_mfma_f32_32x32x16_bf16 v[128:143], v[252:255], v[188:191], v[128:143]
	v_lshl_add_u32 v244, s76, 15, v230
	s_add_i32 s4, s76, 1
	s_cmp_lg_u32 s76, 2
	s_cselect_b32 s76, s4, 0
	s_add_i32 s4, s74, 1
	s_cmp_lg_u32 s74, 2
	s_cselect_b32 s74, s4, 0
	s_add_u32 s22, s22, 0x20000
	s_addc_u32 s23, s23, 0
	s_add_i32 s86, s86, 1
	v_max_f32_e32 v192, v144, v145
	v_max3_f32 v192, v192, v146, v147
	v_max3_f32 v192, v192, v148, v149
	v_max3_f32 v192, v192, v150, v151
	v_max3_f32 v192, v192, v152, v153
	v_max3_f32 v192, v192, v154, v155
	v_max3_f32 v192, v192, v156, v157
	v_max3_f32 v192, v192, v158, v159
	v_max3_f32 v192, v192, v128, v129
	v_max3_f32 v192, v192, v130, v131
	v_max3_f32 v192, v192, v132, v133
	v_max3_f32 v192, v192, v134, v135
	v_max3_f32 v192, v192, v136, v137
	v_max3_f32 v192, v192, v138, v139
	v_max3_f32 v192, v192, v140, v141
	v_max3_f32 v192, v192, v142, v143
	v_mov_b32_e32 v193, v192
	s_nop 1
	v_permlane32_swap_b32_e32 v192, v193
	v_max_f32_e32 v192, v192, v193
	v_sub_f32_e32 v193, v192, v231
	v_cmp_ge_f32_e32 vcc, s38, v193
	s_cmp_eq_u64 vcc, exec
	s_cbranch_scc1 .LBB0_517
	v_max_f32_e32 v234, v231, v192
	v_sub_f32_e32 v192, v231, v234
	v_mul_f32_e32 v192, 0x3e0293ee, v192
	v_exp_f32_e32 v233, v192
	v_mov_b32_e32 v231, v234
	v_mul_f32_e32 v237, 0xbe0293ee, v234
	v_mul_f32_e32 v232, v232, v233
	s_and_saveexec_b64 s[24:25], s[0:1]
	ds_write_b32 v226, v233 offset:128
	s_or_b64 exec, exec, s[24:25]
	s_waitcnt lgkmcnt(0)
	v_add_u32_e32 v192, s21, v210
	ds_read_b128 v[204:207], v192 offset:224
	ds_read_b128 v[200:203], v192 offset:192
	ds_read_b128 v[196:199], v192 offset:160
	ds_read_b128 v[192:195], v192 offset:128
	s_waitcnt lgkmcnt(3)
	v_pk_mul_f32 v[12:13], v[12:13], v[204:205]
	s_waitcnt lgkmcnt(2)
	v_pk_mul_f32 v[8:9], v[8:9], v[200:201]
	s_waitcnt lgkmcnt(1)
	v_pk_mul_f32 v[4:5], v[4:5], v[196:197]
	v_pk_mul_f32 v[14:15], v[14:15], v[206:207]
	v_pk_mul_f32 v[10:11], v[10:11], v[202:203]
	v_pk_mul_f32 v[6:7], v[6:7], v[198:199]
	s_waitcnt lgkmcnt(0)
	v_pk_mul_f32 v[2:3], v[2:3], v[194:195]
	v_pk_mul_f32 v[0:1], v[0:1], v[192:193]
	v_pk_mul_f32 v[124:125], v[124:125], v[204:205]
	v_pk_mul_f32 v[120:121], v[120:121], v[200:201]
	v_pk_mul_f32 v[116:117], v[116:117], v[196:197]
	v_pk_mul_f32 v[126:127], v[126:127], v[206:207]
	v_pk_mul_f32 v[122:123], v[122:123], v[202:203]
	v_pk_mul_f32 v[118:119], v[118:119], v[198:199]
	v_pk_mul_f32 v[114:115], v[114:115], v[194:195]
	v_pk_mul_f32 v[112:113], v[112:113], v[192:193]
	v_pk_mul_f32 v[108:109], v[108:109], v[204:205]
	v_pk_mul_f32 v[104:105], v[104:105], v[200:201]
	v_pk_mul_f32 v[100:101], v[100:101], v[196:197]
	v_pk_mul_f32 v[110:111], v[110:111], v[206:207]
	v_pk_mul_f32 v[106:107], v[106:107], v[202:203]
	v_pk_mul_f32 v[102:103], v[102:103], v[198:199]
	v_pk_mul_f32 v[98:99], v[98:99], v[194:195]
	v_pk_mul_f32 v[96:97], v[96:97], v[192:193]
	v_pk_mul_f32 v[92:93], v[92:93], v[204:205]
	v_pk_mul_f32 v[88:89], v[88:89], v[200:201]
	v_pk_mul_f32 v[84:85], v[84:85], v[196:197]
	v_pk_mul_f32 v[94:95], v[94:95], v[206:207]
	v_pk_mul_f32 v[90:91], v[90:91], v[202:203]
	v_pk_mul_f32 v[86:87], v[86:87], v[198:199]
	v_pk_mul_f32 v[82:83], v[82:83], v[194:195]
	v_pk_mul_f32 v[80:81], v[80:81], v[192:193]
	v_pk_mul_f32 v[76:77], v[76:77], v[204:205]
	v_pk_mul_f32 v[72:73], v[72:73], v[200:201]
	v_pk_mul_f32 v[68:69], v[68:69], v[196:197]
	v_pk_mul_f32 v[78:79], v[78:79], v[206:207]
	v_pk_mul_f32 v[74:75], v[74:75], v[202:203]
	v_pk_mul_f32 v[70:71], v[70:71], v[198:199]
	v_pk_mul_f32 v[66:67], v[66:67], v[194:195]
	v_pk_mul_f32 v[64:65], v[64:65], v[192:193]
	v_pk_mul_f32 v[60:61], v[60:61], v[204:205]
	v_pk_mul_f32 v[56:57], v[56:57], v[200:201]
	v_pk_mul_f32 v[52:53], v[52:53], v[196:197]
	v_pk_mul_f32 v[62:63], v[62:63], v[206:207]
	v_pk_mul_f32 v[58:59], v[58:59], v[202:203]
	v_pk_mul_f32 v[54:55], v[54:55], v[198:199]
	v_pk_mul_f32 v[50:51], v[50:51], v[194:195]
	v_pk_mul_f32 v[48:49], v[48:49], v[192:193]
	v_pk_mul_f32 v[44:45], v[44:45], v[204:205]
	v_pk_mul_f32 v[40:41], v[40:41], v[200:201]
	v_pk_mul_f32 v[36:37], v[36:37], v[196:197]
	v_pk_mul_f32 v[46:47], v[46:47], v[206:207]
	v_pk_mul_f32 v[42:43], v[42:43], v[202:203]
	v_pk_mul_f32 v[38:39], v[38:39], v[198:199]
	v_pk_mul_f32 v[34:35], v[34:35], v[194:195]
	v_pk_mul_f32 v[32:33], v[32:33], v[192:193]
	v_pk_mul_f32 v[28:29], v[28:29], v[204:205]
	v_pk_mul_f32 v[24:25], v[24:25], v[200:201]
	v_pk_mul_f32 v[20:21], v[20:21], v[196:197]
	v_pk_mul_f32 v[30:31], v[30:31], v[206:207]
	v_pk_mul_f32 v[26:27], v[26:27], v[202:203]
	v_pk_mul_f32 v[22:23], v[22:23], v[198:199]
	v_pk_mul_f32 v[18:19], v[18:19], v[194:195]
	v_pk_mul_f32 v[16:17], v[16:17], v[192:193]
.LBB0_517:
	v_fmamk_f32 v144, v144, 0x3e0293ee, v237
	v_fmamk_f32 v145, v145, 0x3e0293ee, v237
	v_fmamk_f32 v146, v146, 0x3e0293ee, v237
	v_fmamk_f32 v147, v147, 0x3e0293ee, v237
	v_fmamk_f32 v148, v148, 0x3e0293ee, v237
	v_fmamk_f32 v149, v149, 0x3e0293ee, v237
	v_fmamk_f32 v150, v150, 0x3e0293ee, v237
	v_fmamk_f32 v151, v151, 0x3e0293ee, v237
	v_fmamk_f32 v152, v152, 0x3e0293ee, v237
	v_fmamk_f32 v153, v153, 0x3e0293ee, v237
	v_fmamk_f32 v154, v154, 0x3e0293ee, v237
	v_fmamk_f32 v155, v155, 0x3e0293ee, v237
	v_fmamk_f32 v156, v156, 0x3e0293ee, v237
	v_fmamk_f32 v157, v157, 0x3e0293ee, v237
	v_fmamk_f32 v158, v158, 0x3e0293ee, v237
	v_fmamk_f32 v159, v159, 0x3e0293ee, v237
	v_fmamk_f32 v128, v128, 0x3e0293ee, v237
	v_fmamk_f32 v129, v129, 0x3e0293ee, v237
	v_fmamk_f32 v130, v130, 0x3e0293ee, v237
	v_fmamk_f32 v131, v131, 0x3e0293ee, v237
	v_fmamk_f32 v132, v132, 0x3e0293ee, v237
	v_fmamk_f32 v133, v133, 0x3e0293ee, v237
	v_fmamk_f32 v134, v134, 0x3e0293ee, v237
	v_fmamk_f32 v135, v135, 0x3e0293ee, v237
	v_fmamk_f32 v136, v136, 0x3e0293ee, v237
	v_fmamk_f32 v137, v137, 0x3e0293ee, v237
	v_fmamk_f32 v138, v138, 0x3e0293ee, v237
	v_fmamk_f32 v139, v139, 0x3e0293ee, v237
	v_fmamk_f32 v140, v140, 0x3e0293ee, v237
	v_fmamk_f32 v141, v141, 0x3e0293ee, v237
	v_fmamk_f32 v142, v142, 0x3e0293ee, v237
	v_fmamk_f32 v192, v143, 0x3e0293ee, v237
	v_exp_f32_e32 v143, v144
	v_exp_f32_e32 v145, v145
	v_exp_f32_e32 v146, v146
	v_exp_f32_e32 v147, v147
	v_exp_f32_e32 v148, v148
	v_exp_f32_e32 v193, v128
	v_exp_f32_e32 v149, v149
	v_add_f32_e32 v128, v145, v143
	v_exp_f32_e32 v150, v150
	v_add_f32_e32 v128, v146, v128
	v_exp_f32_e32 v151, v151
	v_add_f32_e32 v128, v147, v128
	v_exp_f32_e32 v152, v152
	v_add_f32_e32 v128, v148, v128
	v_exp_f32_e32 v153, v153
	v_add_f32_e32 v128, v149, v128
	v_exp_f32_e32 v154, v154
	v_add_f32_e32 v128, v150, v128
	v_exp_f32_e32 v155, v155
	v_add_f32_e32 v128, v151, v128
	v_exp_f32_e32 v156, v156
	v_add_f32_e32 v128, v152, v128
	v_exp_f32_e32 v157, v157
	v_add_f32_e32 v128, v153, v128
	v_exp_f32_e32 v158, v158
	v_add_f32_e32 v128, v154, v128
	v_exp_f32_e32 v159, v159
	v_add_f32_e32 v128, v155, v128
	v_add_f32_e32 v128, v156, v128
	v_exp_f32_e32 v194, v129
	v_add_f32_e32 v128, v157, v128
	v_exp_f32_e32 v195, v130
	v_add_f32_e32 v128, v158, v128
	v_exp_f32_e32 v196, v131
	v_add_f32_e32 v128, v159, v128
	v_exp_f32_e32 v197, v132
	v_add_f32_e32 v128, v193, v128
	v_exp_f32_e32 v198, v133
	v_add_f32_e32 v128, v194, v128
	v_exp_f32_e32 v199, v134
	v_add_f32_e32 v128, v195, v128
	v_exp_f32_e32 v135, v135
	v_add_f32_e32 v128, v196, v128
	v_exp_f32_e32 v200, v136
	v_add_f32_e32 v128, v197, v128
	v_exp_f32_e32 v201, v137
	v_add_f32_e32 v128, v198, v128
	v_exp_f32_e32 v202, v138
	v_add_f32_e32 v128, v199, v128
	v_exp_f32_e32 v203, v139
	v_add_f32_e32 v128, v135, v128
	v_exp_f32_e32 v204, v140
	v_add_f32_e32 v128, v200, v128
	v_exp_f32_e32 v205, v141
	v_add_f32_e32 v128, v201, v128
	v_exp_f32_e32 v206, v142
	v_add_f32_e32 v128, v202, v128
	v_exp_f32_e32 v192, v192
	v_add_f32_e32 v128, v203, v128
	v_add_f32_e32 v128, v204, v128
	v_add_f32_e32 v128, v205, v128
	v_add_f32_e32 v128, v206, v128
	v_add_f32_e32 v128, v192, v128
	v_add_f32_e32 v144, v232, v128
	v_cvt_pk_bf16_f32 v128, v143, v145
	v_cvt_pk_bf16_f32 v129, v146, v147
	v_cvt_pk_bf16_f32 v130, v148, v149
	v_cvt_pk_bf16_f32 v131, v150, v151
	v_cvt_pk_bf16_f32 v136, v152, v153
	v_cvt_pk_bf16_f32 v137, v154, v155
	v_cvt_pk_bf16_f32 v138, v156, v157
	v_cvt_pk_bf16_f32 v139, v158, v159
	v_cvt_pk_bf16_f32 v132, v193, v194
	v_cvt_pk_bf16_f32 v133, v195, v196
	v_cvt_pk_bf16_f32 v134, v197, v198
	v_cvt_pk_bf16_f32 v135, v199, v135
	v_cvt_pk_bf16_f32 v140, v200, v201
	v_cvt_pk_bf16_f32 v141, v202, v203
	v_cvt_pk_bf16_f32 v142, v204, v205
	v_cvt_pk_bf16_f32 v143, v206, v192
	ds_read_b64_tr_b16 v[146:147], v244 offset:0
	ds_read_b64_tr_b16 v[148:149], v244 offset:4096
	ds_read_b64_tr_b16 v[150:151], v244 offset:512
	ds_read_b64_tr_b16 v[152:153], v244 offset:4608
	ds_read_b64_tr_b16 v[154:155], v244 offset:1024
	ds_read_b64_tr_b16 v[156:157], v244 offset:5120
	ds_read_b64_tr_b16 v[192:193], v244 offset:1536
	ds_read_b64_tr_b16 v[194:195], v244 offset:5632
	ds_read_b64_tr_b16 v[196:197], v244 offset:2048
	ds_read_b64_tr_b16 v[198:199], v244 offset:6144
	ds_read_b64_tr_b16 v[200:201], v244 offset:2560
	ds_read_b64_tr_b16 v[202:203], v244 offset:6656
	ds_read_b64_tr_b16 v[204:205], v244 offset:3072
	ds_read_b64_tr_b16 v[206:207], v244 offset:7168
	ds_read_b64_tr_b16 v[232:233], v244 offset:3584
	ds_read_b64_tr_b16 v[234:235], v244 offset:7680
	s_waitcnt lgkmcnt(12)
	s_nop 0
	v_mfma_f32_32x32x16_bf16 v[0:15], v[128:131], v[146:149], v[0:15]
	ds_read_b64_tr_b16 v[240:241], v244 offset:8192
	ds_read_b64_tr_b16 v[242:243], v244 offset:12288
	v_mfma_f32_32x32x16_bf16 v[112:127], v[128:131], v[150:153], v[112:127]
	ds_read_b64_tr_b16 v[146:147], v244 offset:8704
	ds_read_b64_tr_b16 v[148:149], v244 offset:12800
	s_waitcnt lgkmcnt(12)
	v_mfma_f32_32x32x16_bf16 v[96:111], v[128:131], v[154:157], v[96:111]
	ds_read_b64_tr_b16 v[150:151], v244 offset:9216
	ds_read_b64_tr_b16 v[152:153], v244 offset:13312
	v_mfma_f32_32x32x16_bf16 v[80:95], v[128:131], v[192:195], v[80:95]
	ds_read_b64_tr_b16 v[154:155], v244 offset:9728
	ds_read_b64_tr_b16 v[156:157], v244 offset:13824
	s_waitcnt lgkmcnt(12)
	v_mfma_f32_32x32x16_bf16 v[64:79], v[128:131], v[196:199], v[64:79]
	ds_read_b64_tr_b16 v[192:193], v244 offset:10240
	ds_read_b64_tr_b16 v[194:195], v244 offset:14336
	v_mfma_f32_32x32x16_bf16 v[48:63], v[128:131], v[200:203], v[48:63]
	ds_read_b64_tr_b16 v[196:197], v244 offset:10752
	ds_read_b64_tr_b16 v[198:199], v244 offset:14848
	s_waitcnt lgkmcnt(12)
	v_mfma_f32_32x32x16_bf16 v[32:47], v[128:131], v[204:207], v[32:47]
	ds_read_b64_tr_b16 v[200:201], v244 offset:11264
	ds_read_b64_tr_b16 v[202:203], v244 offset:15360
	v_mfma_f32_32x32x16_bf16 v[16:31], v[128:131], v[232:235], v[16:31]
	ds_read_b64_tr_b16 v[204:205], v244 offset:11776
	ds_read_b64_tr_b16 v[206:207], v244 offset:15872
	s_waitcnt lgkmcnt(12)
	v_mfma_f32_32x32x16_bf16 v[0:15], v[136:139], v[240:243], v[0:15]
	ds_read_b64_tr_b16 v[232:233], v244 offset:16384
	ds_read_b64_tr_b16 v[234:235], v244 offset:20480
	v_mfma_f32_32x32x16_bf16 v[112:127], v[136:139], v[146:149], v[112:127]
	ds_read_b64_tr_b16 v[240:241], v244 offset:16896
	ds_read_b64_tr_b16 v[242:243], v244 offset:20992
	s_waitcnt lgkmcnt(12)
	v_mfma_f32_32x32x16_bf16 v[96:111], v[136:139], v[150:153], v[96:111]
	ds_read_b64_tr_b16 v[146:147], v244 offset:17408
	ds_read_b64_tr_b16 v[148:149], v244 offset:21504
	v_mfma_f32_32x32x16_bf16 v[80:95], v[136:139], v[154:157], v[80:95]
	ds_read_b64_tr_b16 v[150:151], v244 offset:17920
	ds_read_b64_tr_b16 v[152:153], v244 offset:22016
	s_waitcnt lgkmcnt(12)
	v_mfma_f32_32x32x16_bf16 v[64:79], v[136:139], v[192:195], v[64:79]
	ds_read_b64_tr_b16 v[154:155], v244 offset:18432
	ds_read_b64_tr_b16 v[156:157], v244 offset:22528
	v_mfma_f32_32x32x16_bf16 v[48:63], v[136:139], v[196:199], v[48:63]
	ds_read_b64_tr_b16 v[192:193], v244 offset:18944
	ds_read_b64_tr_b16 v[194:195], v244 offset:23040
	s_waitcnt lgkmcnt(12)
	v_mfma_f32_32x32x16_bf16 v[32:47], v[136:139], v[200:203], v[32:47]
	ds_read_b64_tr_b16 v[196:197], v244 offset:19456
	ds_read_b64_tr_b16 v[198:199], v244 offset:23552
	v_mfma_f32_32x32x16_bf16 v[16:31], v[136:139], v[204:207], v[16:31]
	ds_read_b64_tr_b16 v[200:201], v244 offset:19968
	ds_read_b64_tr_b16 v[202:203], v244 offset:24064
	s_waitcnt lgkmcnt(12)
	v_mfma_f32_32x32x16_bf16 v[0:15], v[132:135], v[232:235], v[0:15]
	ds_read_b64_tr_b16 v[204:205], v244 offset:24576
	ds_read_b64_tr_b16 v[206:207], v244 offset:28672
	v_mfma_f32_32x32x16_bf16 v[112:127], v[132:135], v[240:243], v[112:127]
	ds_read_b64_tr_b16 v[232:233], v244 offset:25088
	ds_read_b64_tr_b16 v[234:235], v244 offset:29184
	s_waitcnt lgkmcnt(12)
	v_mfma_f32_32x32x16_bf16 v[96:111], v[132:135], v[146:149], v[96:111]
	ds_read_b64_tr_b16 v[240:241], v244 offset:25600
	ds_read_b64_tr_b16 v[242:243], v244 offset:29696
	v_mfma_f32_32x32x16_bf16 v[80:95], v[132:135], v[150:153], v[80:95]
	ds_read_b64_tr_b16 v[146:147], v244 offset:26112
	ds_read_b64_tr_b16 v[148:149], v244 offset:30208
	s_waitcnt lgkmcnt(12)
	v_mfma_f32_32x32x16_bf16 v[64:79], v[132:135], v[154:157], v[64:79]
	ds_read_b64_tr_b16 v[150:151], v244 offset:26624
	ds_read_b64_tr_b16 v[152:153], v244 offset:30720
	v_mfma_f32_32x32x16_bf16 v[48:63], v[132:135], v[192:195], v[48:63]
	ds_read_b64_tr_b16 v[154:155], v244 offset:27136
	ds_read_b64_tr_b16 v[156:157], v244 offset:31232
	s_waitcnt lgkmcnt(12)
	v_mfma_f32_32x32x16_bf16 v[32:47], v[132:135], v[196:199], v[32:47]
	ds_read_b64_tr_b16 v[192:193], v244 offset:27648
	ds_read_b64_tr_b16 v[194:195], v244 offset:31744
	v_mfma_f32_32x32x16_bf16 v[16:31], v[132:135], v[200:203], v[16:31]
	ds_read_b64_tr_b16 v[196:197], v244 offset:28160
	ds_read_b64_tr_b16 v[198:199], v244 offset:32256
	s_waitcnt lgkmcnt(12)
	v_mfma_f32_32x32x16_bf16 v[0:15], v[140:143], v[204:207], v[0:15]
	v_mfma_f32_32x32x16_bf16 v[112:127], v[140:143], v[232:235], v[112:127]
	s_waitcnt lgkmcnt(8)
	v_mfma_f32_32x32x16_bf16 v[96:111], v[140:143], v[240:243], v[96:111]
	v_mfma_f32_32x32x16_bf16 v[80:95], v[140:143], v[146:149], v[80:95]
	s_waitcnt lgkmcnt(4)
	v_mfma_f32_32x32x16_bf16 v[64:79], v[140:143], v[150:153], v[64:79]
	v_mfma_f32_32x32x16_bf16 v[48:63], v[140:143], v[154:157], v[48:63]
	s_cmp_eq_u32 s22, 0x800000
	s_waitcnt lgkmcnt(0)
	v_mfma_f32_32x32x16_bf16 v[32:47], v[140:143], v[192:195], v[32:47]
	v_mfma_f32_32x32x16_bf16 v[16:31], v[140:143], v[196:199], v[16:31]
	s_cbranch_scc1 .LBB0_521
	v_mov_b32_e32 v232, v144
	s_cmp_eq_u32 s22, 0x7e0000
	s_mov_b64 s[4:5], -1
	s_cbranch_scc1 .LBB0_510

.LBB0_906:
	s_lshl_b32 s4, s80, 14
	v_add3_u32 v236, s4, v221, v220
	ds_read_b128 v[192:195], v236
	ds_read_b128 v[196:199], v236 offset:8192
	v_add3_u32 v236, s4, v222, v220
	ds_read_b128 v[200:203], v236
	ds_read_b128 v[204:207], v236 offset:8192
	v_add3_u32 v236, s4, v223, v220
	ds_read_b128 v[240:243], v236
	ds_read_b128 v[244:247], v236 offset:8192
	v_add3_u32 v236, s4, v225, v220
	ds_read_b128 v[248:251], v236
	ds_read_b128 v[252:255], v236 offset:8192
	s_waitcnt lgkmcnt(7)
	v_mfma_f32_32x32x16_bf16 v[144:159], v[192:195], v[160:163], 0
	s_waitcnt lgkmcnt(6)
	v_mfma_f32_32x32x16_bf16 v[128:143], v[196:199], v[160:163], 0
	v_add3_u32 v236, s4, v226, v220
	ds_read_b128 v[192:195], v236
	ds_read_b128 v[196:199], v236 offset:8192
	s_waitcnt lgkmcnt(7)
	v_mfma_f32_32x32x16_bf16 v[144:159], v[200:203], v[164:167], v[144:159]
	s_waitcnt lgkmcnt(6)
	v_mfma_f32_32x32x16_bf16 v[128:143], v[204:207], v[164:167], v[128:143]
	v_add3_u32 v236, s4, v227, v220
	ds_read_b128 v[200:203], v236
	ds_read_b128 v[204:207], v236 offset:8192
	s_waitcnt lgkmcnt(7)
	v_mfma_f32_32x32x16_bf16 v[144:159], v[240:243], v[168:171], v[144:159]
	s_waitcnt lgkmcnt(6)
	v_mfma_f32_32x32x16_bf16 v[128:143], v[244:247], v[168:171], v[128:143]
	v_add3_u32 v236, s4, v228, v220
	ds_read_b128 v[240:243], v236
	ds_read_b128 v[244:247], v236 offset:8192
	s_waitcnt lgkmcnt(7)
	v_mfma_f32_32x32x16_bf16 v[144:159], v[248:251], v[172:175], v[144:159]
	s_waitcnt lgkmcnt(6)
	v_mfma_f32_32x32x16_bf16 v[128:143], v[252:255], v[172:175], v[128:143]
	v_add3_u32 v236, s4, v229, v220
	ds_read_b128 v[248:251], v236
	ds_read_b128 v[252:255], v236 offset:8192
	s_waitcnt lgkmcnt(7)
	v_mfma_f32_32x32x16_bf16 v[144:159], v[192:195], v[176:179], v[144:159]
	s_waitcnt lgkmcnt(6)
	v_mfma_f32_32x32x16_bf16 v[128:143], v[196:199], v[176:179], v[128:143]
	s_waitcnt lgkmcnt(5)
	v_mfma_f32_32x32x16_bf16 v[144:159], v[200:203], v[180:183], v[144:159]
	s_waitcnt lgkmcnt(4)
	v_mfma_f32_32x32x16_bf16 v[128:143], v[204:207], v[180:183], v[128:143]
	s_waitcnt lgkmcnt(3)
	v_mfma_f32_32x32x16_bf16 v[144:159], v[240:243], v[184:187], v[144:159]
	s_waitcnt lgkmcnt(2)
	v_mfma_f32_32x32x16_bf16 v[128:143], v[244:247], v[184:187], v[128:143]
	s_waitcnt lgkmcnt(1)
	v_mfma_f32_32x32x16_bf16 v[144:159], v[248:251], v[188:191], v[144:159]
	s_waitcnt lgkmcnt(0)
	v_mfma_f32_32x32x16_bf16 v[128:143], v[252:255], v[188:191], v[128:143]
	v_max_f32_e32 v194, v231, v231
	v_lshl_add_u32 v244, s80, 15, v230
	s_add_i32 s4, s80, 1
	s_cmp_lg_u32 s80, 2
	s_cselect_b32 s80, s4, 0
	s_add_i32 s4, s78, 1
	s_cmp_lg_u32 s78, 2
	s_cselect_b32 s78, s4, 0
	s_add_u32 s22, s22, 0x20000
	s_addc_u32 s23, s23, 0
	s_add_i32 s86, s86, 1
	v_max_f32_e32 v192, v144, v145
	v_max3_f32 v192, v192, v146, v147
	v_max3_f32 v192, v192, v148, v149
	v_max3_f32 v192, v192, v150, v151
	v_max3_f32 v192, v192, v152, v153
	v_max3_f32 v192, v192, v154, v155
	v_max3_f32 v192, v192, v156, v157
	v_max3_f32 v192, v192, v158, v159
	v_max3_f32 v192, v192, v128, v129
	v_max3_f32 v192, v192, v130, v131
	v_max3_f32 v192, v192, v132, v133
	v_max3_f32 v192, v192, v134, v135
	v_max3_f32 v192, v192, v136, v137
	v_max3_f32 v192, v192, v138, v139
	v_max3_f32 v192, v192, v140, v141
	v_max3_f32 v192, v192, v142, v143
	v_mov_b32_e32 v193, v192
	s_nop 1
	v_permlane32_swap_b32_e32 v192, v193
	v_max_f32_e32 v192, v192, v193
	v_sub_f32_e32 v193, v192, v231
	v_cmp_ge_f32_e32 vcc, s42, v193
	s_cmp_eq_u64 vcc, exec
	s_cbranch_scc1 .LBB0_910
	v_max_f32_e32 v234, v194, v192
	v_sub_f32_e32 v192, v231, v234
	v_mul_f32_e32 v192, 0x3e0293ee, v192
	v_exp_f32_e32 v233, v192
	v_mov_b32_e32 v231, v234
	v_mul_f32_e32 v237, 0xbe0293ee, v234
	v_mul_f32_e32 v232, v232, v233
	s_and_saveexec_b64 s[24:25], s[0:1]
	ds_write_b32 v224, v233 offset:128
	s_or_b64 exec, exec, s[24:25]
	s_waitcnt lgkmcnt(0)
	v_add_u32_e32 v192, s21, v210
	ds_read_b128 v[204:207], v192 offset:224
	ds_read_b128 v[200:203], v192 offset:192
	ds_read_b128 v[196:199], v192 offset:160
	ds_read_b128 v[192:195], v192 offset:128
	s_waitcnt lgkmcnt(3)
	v_pk_mul_f32 v[12:13], v[12:13], v[204:205]
	s_waitcnt lgkmcnt(2)
	v_pk_mul_f32 v[8:9], v[8:9], v[200:201]
	s_waitcnt lgkmcnt(1)
	v_pk_mul_f32 v[4:5], v[4:5], v[196:197]
	v_pk_mul_f32 v[14:15], v[14:15], v[206:207]
	v_pk_mul_f32 v[10:11], v[10:11], v[202:203]
	v_pk_mul_f32 v[6:7], v[6:7], v[198:199]
	s_waitcnt lgkmcnt(0)
	v_pk_mul_f32 v[2:3], v[2:3], v[194:195]
	v_pk_mul_f32 v[0:1], v[0:1], v[192:193]
	v_pk_mul_f32 v[124:125], v[124:125], v[204:205]
	v_pk_mul_f32 v[120:121], v[120:121], v[200:201]
	v_pk_mul_f32 v[116:117], v[116:117], v[196:197]
	v_pk_mul_f32 v[126:127], v[126:127], v[206:207]
	v_pk_mul_f32 v[122:123], v[122:123], v[202:203]
	v_pk_mul_f32 v[118:119], v[118:119], v[198:199]
	v_pk_mul_f32 v[114:115], v[114:115], v[194:195]
	v_pk_mul_f32 v[112:113], v[112:113], v[192:193]
	v_pk_mul_f32 v[108:109], v[108:109], v[204:205]
	v_pk_mul_f32 v[104:105], v[104:105], v[200:201]
	v_pk_mul_f32 v[100:101], v[100:101], v[196:197]
	v_pk_mul_f32 v[110:111], v[110:111], v[206:207]
	v_pk_mul_f32 v[106:107], v[106:107], v[202:203]
	v_pk_mul_f32 v[102:103], v[102:103], v[198:199]
	v_pk_mul_f32 v[98:99], v[98:99], v[194:195]
	v_pk_mul_f32 v[96:97], v[96:97], v[192:193]
	v_pk_mul_f32 v[92:93], v[92:93], v[204:205]
	v_pk_mul_f32 v[88:89], v[88:89], v[200:201]
	v_pk_mul_f32 v[84:85], v[84:85], v[196:197]
	v_pk_mul_f32 v[94:95], v[94:95], v[206:207]
	v_pk_mul_f32 v[90:91], v[90:91], v[202:203]
	v_pk_mul_f32 v[86:87], v[86:87], v[198:199]
	v_pk_mul_f32 v[82:83], v[82:83], v[194:195]
	v_pk_mul_f32 v[80:81], v[80:81], v[192:193]
	v_pk_mul_f32 v[76:77], v[76:77], v[204:205]
	v_pk_mul_f32 v[72:73], v[72:73], v[200:201]
	v_pk_mul_f32 v[68:69], v[68:69], v[196:197]
	v_pk_mul_f32 v[78:79], v[78:79], v[206:207]
	v_pk_mul_f32 v[74:75], v[74:75], v[202:203]
	v_pk_mul_f32 v[70:71], v[70:71], v[198:199]
	v_pk_mul_f32 v[66:67], v[66:67], v[194:195]
	v_pk_mul_f32 v[64:65], v[64:65], v[192:193]
	v_pk_mul_f32 v[60:61], v[60:61], v[204:205]
	v_pk_mul_f32 v[56:57], v[56:57], v[200:201]
	v_pk_mul_f32 v[52:53], v[52:53], v[196:197]
	v_pk_mul_f32 v[62:63], v[62:63], v[206:207]
	v_pk_mul_f32 v[58:59], v[58:59], v[202:203]
	v_pk_mul_f32 v[54:55], v[54:55], v[198:199]
	v_pk_mul_f32 v[50:51], v[50:51], v[194:195]
	v_pk_mul_f32 v[48:49], v[48:49], v[192:193]
	v_pk_mul_f32 v[44:45], v[44:45], v[204:205]
	v_pk_mul_f32 v[40:41], v[40:41], v[200:201]
	v_pk_mul_f32 v[36:37], v[36:37], v[196:197]
	v_pk_mul_f32 v[46:47], v[46:47], v[206:207]
	v_pk_mul_f32 v[42:43], v[42:43], v[202:203]
	v_pk_mul_f32 v[38:39], v[38:39], v[198:199]
	v_pk_mul_f32 v[34:35], v[34:35], v[194:195]
	v_pk_mul_f32 v[32:33], v[32:33], v[192:193]
	v_pk_mul_f32 v[28:29], v[28:29], v[204:205]
	v_pk_mul_f32 v[24:25], v[24:25], v[200:201]
	v_pk_mul_f32 v[20:21], v[20:21], v[196:197]
	v_pk_mul_f32 v[30:31], v[30:31], v[206:207]
	v_pk_mul_f32 v[26:27], v[26:27], v[202:203]
	v_pk_mul_f32 v[22:23], v[22:23], v[198:199]
	v_pk_mul_f32 v[18:19], v[18:19], v[194:195]
	v_pk_mul_f32 v[16:17], v[16:17], v[192:193]
